# NSA flash loops: K-fragment LDS reads issued five deep with counted lgkmcnt instead of read-wait-MFMA eight times
# speedup vs baseline: 1.0025x; 1.0025x over previous
.LBB0_1564:
	v_add3_u32 v80, s11, v106, v107
	ds_read_b128 v[10:13], v80
	ds_read_b128 v[220:223], v80 offset:4608
	ds_read_b128 v[240:243], v80 offset:32
	ds_read_b128 v[244:247], v80 offset:4640
	ds_read_b128 v[248:251], v80 offset:64
	v_xor_b32_e32 v48, 0x80000000, v93
	v_mov_b32_e32 v49, v48
	v_mov_b32_e32 v50, v48
	v_mov_b32_e32 v51, v48
	v_mov_b32_e32 v52, v48
	v_mov_b32_e32 v53, v48
	v_mov_b32_e32 v54, v48
	v_mov_b32_e32 v55, v48
	v_mov_b32_e32 v56, v48
	v_mov_b32_e32 v57, v48
	v_mov_b32_e32 v58, v48
	v_mov_b32_e32 v59, v48
	v_mov_b32_e32 v60, v48
	v_mov_b32_e32 v61, v48
	v_mov_b32_e32 v62, v48
	v_mov_b32_e32 v63, v48
	s_cmp_le_i32 s10, s9
	s_waitcnt lgkmcnt(4)
	v_mfma_f32_32x32x16_bf16 v[64:79], v[10:13], v[144:147], v[48:63]
	ds_read_b128 v[10:13], v80 offset:4672
	s_waitcnt lgkmcnt(4)
	v_mfma_f32_32x32x16_bf16 v[48:63], v[220:223], v[144:147], v[48:63]
	ds_read_b128 v[220:223], v80 offset:96
	s_waitcnt lgkmcnt(4)
	v_mfma_f32_32x32x16_bf16 v[64:79], v[240:243], v[148:151], v[64:79]
	ds_read_b128 v[240:243], v80 offset:4704
	s_waitcnt lgkmcnt(4)
	v_mfma_f32_32x32x16_bf16 v[48:63], v[244:247], v[148:151], v[48:63]
	s_waitcnt lgkmcnt(3)
	v_mfma_f32_32x32x16_bf16 v[64:79], v[248:251], v[152:155], v[64:79]
	s_waitcnt lgkmcnt(2)
	v_mfma_f32_32x32x16_bf16 v[48:63], v[10:13], v[152:155], v[48:63]
	s_waitcnt lgkmcnt(1)
	v_mfma_f32_32x32x16_bf16 v[64:79], v[220:223], v[156:159], v[64:79]
	s_waitcnt lgkmcnt(0)
	v_mfma_f32_32x32x16_bf16 v[48:63], v[240:243], v[156:159], v[48:63]
	s_cbranch_scc1 .LBB0_1566
	v_add_u32_e32 v10, s10, v108
	v_cmp_le_i32_e32 vcc, v10, v109
	v_add_u32_e32 v11, 0x21f, v10
	s_nop 4
	v_cndmask_b32_e32 v64, v236, v64, vcc
	v_cmp_le_i32_e32 vcc, v11, v188
	v_add_u32_e32 v11, 16, v10
	s_nop 0
	v_cndmask_b32_e32 v48, v236, v48, vcc
	v_cmp_le_i32_e32 vcc, v11, v109
	v_add_u32_e32 v11, 0x22f, v10
	s_nop 0
	v_cndmask_b32_e32 v65, v236, v65, vcc
	v_cmp_le_i32_e32 vcc, v11, v188
	v_add_u32_e32 v11, 32, v10
	s_nop 0
	v_cndmask_b32_e32 v49, v236, v49, vcc
	v_cmp_le_i32_e32 vcc, v11, v109
	v_add_u32_e32 v11, 0x23f, v10
	s_nop 0
	v_cndmask_b32_e32 v66, v236, v66, vcc
	v_cmp_le_i32_e32 vcc, v11, v188
	v_add_u32_e32 v11, 48, v10
	s_nop 0
	v_cndmask_b32_e32 v50, v236, v50, vcc
	v_cmp_le_i32_e32 vcc, v11, v109
	v_add_u32_e32 v11, 0x80, v10
	s_nop 0
	v_cndmask_b32_e32 v67, v236, v67, vcc
	v_cmp_le_i32_e32 vcc, v10, v112
	s_nop 1
	v_cndmask_b32_e32 v51, v236, v51, vcc
	v_cmp_le_i32_e32 vcc, v11, v109
	v_add_u32_e32 v11, 0x29f, v10
	s_nop 0
	v_cndmask_b32_e32 v68, v236, v68, vcc
	v_cmp_le_i32_e32 vcc, v11, v188
	v_add_u32_e32 v11, 0x90, v10
	s_nop 0
	v_cndmask_b32_e32 v52, v236, v52, vcc
	v_cmp_le_i32_e32 vcc, v11, v109
	v_add_u32_e32 v11, 0x2af, v10
	s_nop 0
	v_cndmask_b32_e32 v69, v236, v69, vcc
	v_cmp_le_i32_e32 vcc, v11, v188
	v_add_u32_e32 v11, 0xa0, v10
	s_nop 0
	v_cndmask_b32_e32 v53, v236, v53, vcc
	v_cmp_le_i32_e32 vcc, v11, v109
	v_add_u32_e32 v11, 0x2bf, v10
	s_nop 0
	v_cndmask_b32_e32 v70, v236, v70, vcc
	v_cmp_le_i32_e32 vcc, v11, v188
	v_add_u32_e32 v11, 0xb0, v10
	s_nop 0
	v_cndmask_b32_e32 v54, v236, v54, vcc
	v_cmp_le_i32_e32 vcc, v11, v109
	v_add_u32_e32 v11, 0x100, v10
	s_nop 0
	v_cndmask_b32_e32 v71, v236, v71, vcc
	v_cmp_le_i32_e32 vcc, v10, v113
	s_nop 1
	v_cndmask_b32_e32 v55, v236, v55, vcc
	v_cmp_le_i32_e32 vcc, v11, v109
	v_add_u32_e32 v11, 0x31f, v10
	s_nop 0
	v_cndmask_b32_e32 v72, v236, v72, vcc
	v_cmp_le_i32_e32 vcc, v11, v188
	v_add_u32_e32 v11, 0x110, v10
	s_nop 0
	v_cndmask_b32_e32 v56, v236, v56, vcc
	v_cmp_le_i32_e32 vcc, v11, v109
	v_add_u32_e32 v11, 0x32f, v10
	s_nop 0
	v_cndmask_b32_e32 v73, v236, v73, vcc
	v_cmp_le_i32_e32 vcc, v11, v188
	v_add_u32_e32 v11, 0x120, v10
	s_nop 0
	v_cndmask_b32_e32 v57, v236, v57, vcc
	v_cmp_le_i32_e32 vcc, v11, v109
	v_add_u32_e32 v11, 0x33f, v10
	s_nop 0
	v_cndmask_b32_e32 v74, v236, v74, vcc
	v_cmp_le_i32_e32 vcc, v11, v188
	v_add_u32_e32 v11, 0x130, v10
	s_nop 0
	v_cndmask_b32_e32 v58, v236, v58, vcc
	v_cmp_le_i32_e32 vcc, v11, v109
	v_add_u32_e32 v11, 0x180, v10
	s_nop 0
	v_cndmask_b32_e32 v75, v236, v75, vcc
	v_cmp_le_i32_e32 vcc, v10, v114
	s_nop 1
	v_cndmask_b32_e32 v59, v236, v59, vcc
	v_cmp_le_i32_e32 vcc, v11, v109
	v_add_u32_e32 v11, 0x39f, v10
	s_nop 0
	v_cndmask_b32_e32 v76, v236, v76, vcc
	v_cmp_le_i32_e32 vcc, v11, v188
	v_add_u32_e32 v11, 0x190, v10
	s_nop 0
	v_cndmask_b32_e32 v60, v236, v60, vcc
	v_cmp_le_i32_e32 vcc, v11, v109
	v_add_u32_e32 v11, 0x3af, v10
	s_nop 0
	v_cndmask_b32_e32 v77, v236, v77, vcc
	v_cmp_le_i32_e32 vcc, v11, v188
	v_add_u32_e32 v11, 0x1a0, v10
	s_nop 0
	v_cndmask_b32_e32 v61, v236, v61, vcc
	v_cmp_le_i32_e32 vcc, v11, v109
	v_add_u32_e32 v11, 0x3bf, v10
	s_nop 0
	v_cndmask_b32_e32 v78, v236, v78, vcc
	v_cmp_le_i32_e32 vcc, v11, v188
	v_add_u32_e32 v11, 0x1b0, v10
	v_add_u32_e32 v10, 0x3cf, v10
	v_cndmask_b32_e32 v62, v236, v62, vcc
	v_cmp_le_i32_e32 vcc, v11, v109
	s_nop 1
	v_cndmask_b32_e32 v79, v236, v79, vcc
	v_cmp_le_i32_e32 vcc, v10, v188
	s_nop 1
	v_cndmask_b32_e32 v63, v236, v63, vcc

.LBB0_1654:
	s_lshr_b32 s66, s80, 3
	s_and_b32 s66, s66, 0x1ffffffc
	v_add_u32_e32 v10, s66, v124
	ds_read_b32 v10, v10
	s_and_b32 s66, s80, 31
	s_waitcnt lgkmcnt(0)
	v_lshrrev_b32_e32 v11, s80, v10
	v_bfe_u32 v10, v10, s66, 1
	v_and_b32_e32 v11, 1, v11
	v_cmp_ne_u32_e32 vcc, 0, v10
	v_cmp_eq_u32_e64 s[66:67], 1, v11
	s_cbranch_vccz .LBB0_1651
	v_add3_u32 v112, s81, v126, v127
	ds_read_b128 v[10:13], v112
	ds_read_b128 v[220:223], v112 offset:4608
	ds_read_b128 v[240:243], v112 offset:32
	ds_read_b128 v[244:247], v112 offset:4640
	ds_read_b128 v[248:251], v112 offset:64
	v_cndmask_b32_e64 v80, v236, -v130, s[66:67]
	v_mov_b32_e32 v81, v80
	v_mov_b32_e32 v82, v80
	v_mov_b32_e32 v83, v80
	v_mov_b32_e32 v84, v80
	v_mov_b32_e32 v85, v80
	v_mov_b32_e32 v86, v80
	v_mov_b32_e32 v87, v80
	v_mov_b32_e32 v88, v80
	v_mov_b32_e32 v89, v80
	v_mov_b32_e32 v90, v80
	v_mov_b32_e32 v91, v80
	v_mov_b32_e32 v92, v80
	v_mov_b32_e32 v93, v80
	v_mov_b32_e32 v94, v80
	v_mov_b32_e32 v95, v80
	s_cmp_lg_u32 s76, s80
	s_waitcnt lgkmcnt(4)
	v_mfma_f32_32x32x16_bf16 v[96:111], v[10:13], v[144:147], v[80:95]
	ds_read_b128 v[10:13], v112 offset:4672
	s_waitcnt lgkmcnt(4)
	v_mfma_f32_32x32x16_bf16 v[80:95], v[220:223], v[144:147], v[80:95]
	ds_read_b128 v[220:223], v112 offset:96
	s_waitcnt lgkmcnt(4)
	v_mfma_f32_32x32x16_bf16 v[96:111], v[240:243], v[148:151], v[96:111]
	ds_read_b128 v[240:243], v112 offset:4704
	s_waitcnt lgkmcnt(4)
	v_mfma_f32_32x32x16_bf16 v[80:95], v[244:247], v[148:151], v[80:95]
	s_waitcnt lgkmcnt(3)
	v_mfma_f32_32x32x16_bf16 v[96:111], v[248:251], v[152:155], v[96:111]
	s_waitcnt lgkmcnt(2)
	v_mfma_f32_32x32x16_bf16 v[80:95], v[10:13], v[152:155], v[80:95]
	s_waitcnt lgkmcnt(1)
	v_mfma_f32_32x32x16_bf16 v[96:111], v[220:223], v[156:159], v[96:111]
	s_waitcnt lgkmcnt(0)
	v_mfma_f32_32x32x16_bf16 v[80:95], v[240:243], v[156:159], v[80:95]
	s_cbranch_scc1 .LBB0_1657
	s_nop 7
	v_cndmask_b32_e64 v10, v96, v236, s[0:1]
	s_nop 1
	v_cndmask_b32_e64 v80, v80, v236, s[2:3]
	v_cndmask_b32_e64 v97, v236, v97, s[4:5]
	v_cndmask_b32_e64 v96, v10, v96, s[4:5]
	v_cndmask_b32_e64 v81, v81, v236, s[6:7]
	v_cndmask_b32_e64 v98, v98, v236, s[8:9]
	v_cndmask_b32_e64 v82, v82, v236, s[10:11]
	v_cndmask_b32_e64 v99, v99, v236, s[12:13]
	v_cndmask_b32_e64 v83, v83, v236, s[14:15]
	v_cndmask_b32_e64 v100, v100, v236, s[16:17]
	v_cndmask_b32_e64 v84, v84, v236, s[18:19]
	v_cndmask_b32_e64 v101, v101, v236, s[20:21]
	v_cndmask_b32_e64 v85, v85, v236, s[22:23]
	v_cndmask_b32_e64 v102, v102, v236, s[24:25]
	v_cndmask_b32_e64 v86, v86, v236, s[26:27]
	v_cndmask_b32_e64 v103, v103, v236, s[28:29]
	v_cndmask_b32_e64 v87, v87, v236, s[30:31]
	v_cndmask_b32_e64 v104, v104, v236, s[34:35]
	v_cndmask_b32_e64 v88, v88, v236, s[36:37]
	v_cndmask_b32_e64 v105, v105, v236, s[38:39]
	v_cndmask_b32_e64 v89, v89, v236, s[40:41]
	v_cndmask_b32_e64 v106, v106, v236, s[42:43]
	v_cndmask_b32_e64 v90, v90, v236, s[44:45]
	v_cndmask_b32_e64 v107, v107, v236, s[46:47]
	v_cndmask_b32_e64 v91, v91, v236, s[48:49]
	v_cndmask_b32_e64 v108, v108, v236, s[50:51]
	v_cndmask_b32_e64 v92, v92, v236, s[52:53]
	v_cndmask_b32_e64 v109, v109, v236, s[54:55]
	v_cndmask_b32_e64 v93, v93, v236, s[56:57]
	v_cndmask_b32_e64 v110, v110, v236, s[58:59]
	v_cndmask_b32_e64 v94, v94, v236, s[60:61]
	v_cndmask_b32_e64 v111, v111, v236, s[62:63]
	v_cndmask_b32_e64 v95, v95, v236, s[64:65]

.LBB0_1666:
	v_add3_u32 v160, s5, v198, v199
	ds_read_b128 v[10:13], v160
	ds_read_b128 v[220:223], v160 offset:4608
	ds_read_b128 v[240:243], v160 offset:32
	ds_read_b128 v[244:247], v160 offset:4640
	ds_read_b128 v[248:251], v160 offset:64
	v_xor_b32_e32 v112, 0x80000000, v204
	v_mov_b32_e32 v113, v112
	v_mov_b32_e32 v114, v112
	v_mov_b32_e32 v115, v112
	v_mov_b32_e32 v116, v112
	v_mov_b32_e32 v117, v112
	v_mov_b32_e32 v118, v112
	v_mov_b32_e32 v119, v112
	v_mov_b32_e32 v120, v112
	v_mov_b32_e32 v121, v112
	v_mov_b32_e32 v122, v112
	v_mov_b32_e32 v123, v112
	v_mov_b32_e32 v124, v112
	v_mov_b32_e32 v125, v112
	v_mov_b32_e32 v126, v112
	v_mov_b32_e32 v127, v112
	s_add_i32 s6, s3, s4
	s_cmp_eq_u32 s6, 11
	s_waitcnt lgkmcnt(4)
	v_mfma_f32_32x32x16_bf16 v[128:143], v[10:13], v[144:147], v[112:127]
	ds_read_b128 v[10:13], v160 offset:4672
	s_cselect_b64 s[0:1], -1, 0
	s_cmp_eq_u32 s6, 3
	s_cselect_b64 s[6:7], -1, 0
	s_or_b64 s[0:1], s[0:1], s[6:7]
	s_andn2_b64 vcc, exec, s[0:1]
	s_waitcnt lgkmcnt(4)
	v_mfma_f32_32x32x16_bf16 v[112:127], v[220:223], v[144:147], v[112:127]
	ds_read_b128 v[220:223], v160 offset:96
	s_waitcnt lgkmcnt(4)
	v_mfma_f32_32x32x16_bf16 v[128:143], v[240:243], v[148:151], v[128:143]
	ds_read_b128 v[240:243], v160 offset:4704
	s_waitcnt lgkmcnt(4)
	v_mfma_f32_32x32x16_bf16 v[112:127], v[244:247], v[148:151], v[112:127]
	s_waitcnt lgkmcnt(3)
	v_mfma_f32_32x32x16_bf16 v[128:143], v[248:251], v[152:155], v[128:143]
	s_waitcnt lgkmcnt(2)
	v_mfma_f32_32x32x16_bf16 v[112:127], v[10:13], v[152:155], v[112:127]
	s_waitcnt lgkmcnt(1)
	v_mfma_f32_32x32x16_bf16 v[128:143], v[220:223], v[156:159], v[128:143]
	s_waitcnt lgkmcnt(0)
	v_mfma_f32_32x32x16_bf16 v[112:127], v[240:243], v[156:159], v[112:127]
	s_cbranch_vccnz .LBB0_1668
	v_cmp_gt_i32_e32 vcc, v203, v188
	v_cmp_lt_i32_e64 s[0:1], v203, v200
	s_or_b64 vcc, vcc, s[0:1]
	v_add_u32_e32 v10, 32, v203
	s_nop 4
	v_cndmask_b32_e32 v128, v128, v236, vcc
	v_cmp_gt_i32_e32 vcc, v10, v188
	v_cmp_lt_i32_e64 s[0:1], v10, v200
	s_or_b64 vcc, vcc, s[0:1]
	v_add_u32_e32 v10, 1, v203
	v_cndmask_b32_e32 v112, v112, v236, vcc
	v_cmp_ge_i32_e32 vcc, v203, v188
	v_cmp_lt_i32_e64 s[0:1], v10, v200
	s_or_b64 vcc, vcc, s[0:1]
	v_add_u32_e32 v10, 33, v203
	v_cndmask_b32_e32 v129, v129, v236, vcc
	v_cmp_gt_i32_e32 vcc, v10, v188
	v_cmp_lt_i32_e64 s[0:1], v10, v200
	s_or_b64 vcc, vcc, s[0:1]
	v_add_u32_e32 v10, 2, v203
	v_cndmask_b32_e32 v113, v113, v236, vcc
	v_cmp_gt_i32_e32 vcc, v10, v188
	v_cmp_lt_i32_e64 s[0:1], v10, v200
	s_or_b64 vcc, vcc, s[0:1]
	v_add_u32_e32 v10, 34, v203
	v_cndmask_b32_e32 v130, v130, v236, vcc
	v_cmp_gt_i32_e32 vcc, v10, v188
	v_cmp_lt_i32_e64 s[0:1], v10, v200
	s_or_b64 vcc, vcc, s[0:1]
	v_add_u32_e32 v10, 3, v203
	v_cndmask_b32_e32 v114, v114, v236, vcc
	v_cmp_gt_i32_e32 vcc, v10, v188
	v_cmp_lt_i32_e64 s[0:1], v10, v200
	s_or_b64 vcc, vcc, s[0:1]
	v_add_u32_e32 v10, 35, v203
	v_cndmask_b32_e32 v131, v131, v236, vcc
	v_cmp_gt_i32_e32 vcc, v10, v188
	v_cmp_lt_i32_e64 s[0:1], v10, v200
	s_or_b64 vcc, vcc, s[0:1]
	v_add_u32_e32 v10, 8, v203
	v_cndmask_b32_e32 v115, v115, v236, vcc
	v_cmp_gt_i32_e32 vcc, v10, v188
	v_cmp_lt_i32_e64 s[0:1], v10, v200
	s_or_b64 vcc, vcc, s[0:1]
	v_add_u32_e32 v10, 40, v203
	v_cndmask_b32_e32 v132, v132, v236, vcc
	v_cmp_gt_i32_e32 vcc, v10, v188
	v_cmp_lt_i32_e64 s[0:1], v10, v200
	s_or_b64 vcc, vcc, s[0:1]
	v_add_u32_e32 v10, 9, v203
	v_cndmask_b32_e32 v116, v116, v236, vcc
	v_cmp_gt_i32_e32 vcc, v10, v188
	v_cmp_lt_i32_e64 s[0:1], v10, v200
	s_or_b64 vcc, vcc, s[0:1]
	v_add_u32_e32 v10, 41, v203
	v_cndmask_b32_e32 v133, v133, v236, vcc
	v_cmp_gt_i32_e32 vcc, v10, v188
	v_cmp_lt_i32_e64 s[0:1], v10, v200
	s_or_b64 vcc, vcc, s[0:1]
	v_add_u32_e32 v10, 10, v203
	v_cndmask_b32_e32 v117, v117, v236, vcc
	v_cmp_gt_i32_e32 vcc, v10, v188
	v_cmp_lt_i32_e64 s[0:1], v10, v200
	s_or_b64 vcc, vcc, s[0:1]
	v_add_u32_e32 v10, 42, v203
	v_cndmask_b32_e32 v134, v134, v236, vcc
	v_cmp_gt_i32_e32 vcc, v10, v188
	v_cmp_lt_i32_e64 s[0:1], v10, v200
	s_or_b64 vcc, vcc, s[0:1]
	v_add_u32_e32 v10, 11, v203
	v_cndmask_b32_e32 v118, v118, v236, vcc
	v_cmp_gt_i32_e32 vcc, v10, v188
	v_cmp_lt_i32_e64 s[0:1], v10, v200
	s_or_b64 vcc, vcc, s[0:1]
	v_add_u32_e32 v10, 43, v203
	v_cndmask_b32_e32 v135, v135, v236, vcc
	v_cmp_gt_i32_e32 vcc, v10, v188
	v_cmp_lt_i32_e64 s[0:1], v10, v200
	s_or_b64 vcc, vcc, s[0:1]
	v_add_u32_e32 v10, 16, v203
	v_cndmask_b32_e32 v119, v119, v236, vcc
	v_cmp_gt_i32_e32 vcc, v10, v188
	v_cmp_lt_i32_e64 s[0:1], v10, v200
	s_or_b64 vcc, vcc, s[0:1]
	v_add_u32_e32 v10, 48, v203
	v_cndmask_b32_e32 v136, v136, v236, vcc
	v_cmp_gt_i32_e32 vcc, v10, v188
	v_cmp_lt_i32_e64 s[0:1], v10, v200
	s_or_b64 vcc, vcc, s[0:1]
	v_add_u32_e32 v10, 17, v203
	v_cndmask_b32_e32 v120, v120, v236, vcc
	v_cmp_gt_i32_e32 vcc, v10, v188
	v_cmp_lt_i32_e64 s[0:1], v10, v200
	s_or_b64 vcc, vcc, s[0:1]
	v_add_u32_e32 v10, 49, v203
	v_cndmask_b32_e32 v137, v137, v236, vcc
	v_cmp_gt_i32_e32 vcc, v10, v188
	v_cmp_lt_i32_e64 s[0:1], v10, v200
	s_or_b64 vcc, vcc, s[0:1]
	v_add_u32_e32 v10, 18, v203
	v_cndmask_b32_e32 v121, v121, v236, vcc
	v_cmp_gt_i32_e32 vcc, v10, v188
	v_cmp_lt_i32_e64 s[0:1], v10, v200
	s_or_b64 vcc, vcc, s[0:1]
	v_add_u32_e32 v10, 50, v203
	v_cndmask_b32_e32 v138, v138, v236, vcc
	v_cmp_gt_i32_e32 vcc, v10, v188
	v_cmp_lt_i32_e64 s[0:1], v10, v200
	s_or_b64 vcc, vcc, s[0:1]
	v_add_u32_e32 v10, 19, v203
	v_cndmask_b32_e32 v122, v122, v236, vcc
	v_cmp_gt_i32_e32 vcc, v10, v188
	v_cmp_lt_i32_e64 s[0:1], v10, v200
	s_or_b64 vcc, vcc, s[0:1]
	v_add_u32_e32 v10, 51, v203
	v_cndmask_b32_e32 v139, v139, v236, vcc
	v_cmp_gt_i32_e32 vcc, v10, v188
	v_cmp_lt_i32_e64 s[0:1], v10, v200
	s_or_b64 vcc, vcc, s[0:1]
	v_add_u32_e32 v10, 24, v203
	v_cndmask_b32_e32 v123, v123, v236, vcc
	v_cmp_gt_i32_e32 vcc, v10, v188
	v_cmp_lt_i32_e64 s[0:1], v10, v200
	s_or_b64 vcc, vcc, s[0:1]
	v_add_u32_e32 v10, 56, v203
	v_cndmask_b32_e32 v140, v140, v236, vcc
	v_cmp_gt_i32_e32 vcc, v10, v188
	v_cmp_lt_i32_e64 s[0:1], v10, v200
	s_or_b64 vcc, vcc, s[0:1]
	v_add_u32_e32 v10, 25, v203
	v_cndmask_b32_e32 v124, v124, v236, vcc
	v_cmp_gt_i32_e32 vcc, v10, v188
	v_cmp_lt_i32_e64 s[0:1], v10, v200
	s_or_b64 vcc, vcc, s[0:1]
	v_add_u32_e32 v10, 57, v203
	v_cndmask_b32_e32 v141, v141, v236, vcc
	v_cmp_gt_i32_e32 vcc, v10, v188
	v_cmp_lt_i32_e64 s[0:1], v10, v200
	s_or_b64 vcc, vcc, s[0:1]
	v_add_u32_e32 v10, 26, v203
	v_cndmask_b32_e32 v125, v125, v236, vcc
	v_cmp_gt_i32_e32 vcc, v10, v188
	v_cmp_lt_i32_e64 s[0:1], v10, v200
	s_or_b64 vcc, vcc, s[0:1]
	v_add_u32_e32 v10, 58, v203
	v_cndmask_b32_e32 v142, v142, v236, vcc
	v_cmp_gt_i32_e32 vcc, v10, v188
	v_cmp_lt_i32_e64 s[0:1], v10, v200
	s_or_b64 vcc, vcc, s[0:1]
	v_add_u32_e32 v10, 27, v203
	v_cndmask_b32_e32 v126, v126, v236, vcc
	v_cmp_gt_i32_e32 vcc, v10, v188
	v_cmp_lt_i32_e64 s[0:1], v10, v200
	s_or_b64 vcc, vcc, s[0:1]
	v_add_u32_e32 v10, 59, v203
	v_cndmask_b32_e32 v143, v143, v236, vcc
	v_cmp_gt_i32_e32 vcc, v10, v188
	v_cmp_lt_i32_e64 s[0:1], v10, v200
	s_or_b64 vcc, vcc, s[0:1]
	v_cndmask_b32_e32 v127, v127, v236, vcc
